# in-proj tile order: column tile rotated within its group of four per round so the three kmax-carrying column tiles fall on different workgroups
# speedup vs baseline: 1.0076x; 1.0076x over previous
;     __host__ __device__ bool next(int i, Unit& u) const {
;         const long L = (long)i * G + c; if (L >= nwg) return false;
;         int wgid = (int)L; { const int q = nwg / NXCD, r = nwg % NXCD, xcd = wgid % NXCD, off = wgid / NXCD; wgid = (xcd < r ? xcd * (q + 1) : r * (q + 1) + (xcd - r) * q) + off; }
;         const int nig = WGM * nN, gid = wgid / nig, fm = gid * WGM, gsz = (nM - fm) < WGM ? (nM - fm) : WGM;
;         u.pm = fm + ((wgid % nig) % gsz); u.pn = (wgid % nig) / gsz; return true;
;     }
.LBB0_173:
	s_ashr_i32 s30, s40, 3
	s_add_i32 s30, s42, s30
	s_ashr_i32 s31, s30, 31
	s_lshr_b32 s31, s31, 25
	s_add_i32 s31, s30, s31
	s_ashr_i32 s40, s31, 7
	s_lshl_b32 s40, s40, 3
	s_sub_i32 s41, 64, s40
	s_min_i32 s41, s41, 8
	s_abs_i32 s42, s41
	v_cvt_f32_u32_e32 v4, s42
	s_sub_i32 s44, 0, s42
	s_and_b32 s31, s31, 0xffffff80
	s_sub_i32 s31, s30, s31
	v_rcp_iflag_f32_e32 v4, v4
	s_abs_i32 s30, s31
	s_xor_b32 s43, s31, s41
	s_ashr_i32 s43, s43, 31
	v_mul_f32_e32 v4, 0x4f7ffffe, v4
	v_cvt_u32_f32_e32 v4, v4
	s_nop 0
	v_readfirstlane_b32 s45, v4
	s_mul_i32 s44, s44, s45
	s_mul_hi_u32 s44, s45, s44
	s_add_i32 s45, s45, s44
	s_mul_hi_u32 s44, s30, s45
	s_mul_i32 s45, s44, s42
	s_sub_i32 s30, s30, s45
	s_add_i32 s50, s44, 1
	s_sub_i32 s45, s30, s42
	s_cmp_ge_u32 s30, s42
	s_cselect_b32 s44, s50, s44
	s_cselect_b32 s30, s45, s30
	s_add_i32 s45, s44, 1
	s_cmp_ge_u32 s30, s42
	s_cselect_b32 s30, s45, s44
	s_xor_b32 s30, s30, s43
	s_sub_i32 s30, s30, s43
	s_mul_i32 s41, s30, s41
	s_sub_i32 s31, s31, s41
	s_add_i32 s40, s40, s31
	s_lshr_b32 s41, s30, 2
	s_add_i32 s41, s41, s30
	s_and_b32 s41, s41, 3
	s_and_b32 s30, s30, 12
	s_or_b32 s30, s30, s41
